# v3 + in-proj phase: rotate each XCD's unit chunk by 3 per round so rope-epilogue (Q/K) units are spread over XCDs
# baseline (speedup 1.0000x reference)
;     __device__ __forceinline__ bool next(int i, Unit& u) const {
;         const long L = (long)i * G + c; if (L >= total) return false;
;         int w = (int)L; { const int q = total / 8, r = total % 8, xcd = w % 8, off = w / 8; w = (xcd < r ? xcd * (q + 1) : r * (q + 1) + (xcd - r) * q) + off; }
;         if (seg_take(s0, w, u)) return true;
;         if (nseg > 1 && seg_take(s1, w, u)) return true;
;         if (nseg > 2 && seg_take(s2, w, u)) return true;
;         if (nseg > 3 && seg_take(s3, w, u)) return true;
;         return false;
.LBB0_664:
	s_add_i32 s13, s14, 1
	s_mul_i32 s2, s13, s33
	v_readlane_b32 s6, v254, 44
	s_mul_hi_i32 s3, s13, s33
	s_add_u32 s2, s2, s6
	s_addc_u32 s3, s3, s92
	v_cmp_gt_i64_e32 vcc, s[2:3], v[176:177]
	s_cbranch_vccnz .LBB0_668
	s_ashr_i32 s3, s2, 31
	s_lshr_b32 s3, s3, 29
	s_add_i32 s3, s2, s3
	s_ashr_i32 s6, s3, 3
	s_and_b32 s3, s3, -8
	s_sub_i32 s2, s2, s3
	s_lshr_b32 s98, s6, 5
	s_mul_i32 s98, s98, 3
	s_add_i32 s2, s2, s98
	s_and_b32 s2, s2, 7
	s_cmp_lt_i32 s2, 0
	s_movk_i32 s3, 0x5c
	s_cselect_b32 s3, s3, 0x5b
	s_mul_i32 s15, s2, s3
	s_add_i32 s15, s15, s6
	s_cmpk_gt_i32 s15, 0xbf
	s_cselect_b64 s[2:3], -1, 0
	s_cmpk_lt_i32 s15, 0xc0
	s_mov_b64 s[6:7], -1
	s_cbranch_scc1 .LBB0_701
	s_add_i32 s28, s15, 0xffffff40
	s_cbranch_execz .LBB0_702
